# GEMM-up epilogue row loop: LDS row reads software-pipelined one row body ahead (wait lands on data fetched a body earlier)
# speedup vs baseline: 1.0020x; 1.0020x over previous
; #define UFOR(v, n) _Pragma("unroll") for (int v = 0; v < (n); ++v)
; #define LDS_BARRIER() do { asm volatile("s_waitcnt lgkmcnt(0)" ::: "memory"); __builtin_amdgcn_s_barrier(); asm volatile("" ::: "memory"); } while (0)
; __device__ __forceinline__ unsigned pk2(float a, float b) { return (unsigned)f2bf(a) | ((unsigned)f2bf(b) << 16); }
; __device__ __forceinline__ float lo2f(unsigned u) { return __uint_as_float(u << 16); }
; __device__ __forceinline__ float hi2f(unsigned u) { return __uint_as_float(u & 0xffff0000u); }
; template <int EPI, int K, int KL> ...
;     ...
;     u16* U = (u16*)smem;
;     LDS_BARRIER();
;     UFOR(ai, 2) UFOR(bj, 2) UFOR(m, 4) {
;       const f32x4 a = acc[ai][bj][m][0], b = acc[ai][bj][m][1];
;       uint4 pk; pk.x = pk2(a[0], a[1]); pk.y = pk2(a[2], a[3]); pk.z = pk2(b[0], b[1]); pk.w = pk2(b[2], b[3]);
;       *(uint4*)(U + (ai * HALF + wr * 64 + m * 16 + fr) * 256 + bj * 128 + wc * 32 + fq * 8) = pk;
;     }
;     LDS_BARRIER();
;     {
;       const int c4 = (tid_ & 31) * 4, rb = tid_ >> 5;
;       const int gc = pn * 128 + c4;
;       float wg[4][3], wv[4][3];
;       UFOR(q, 4) UFOR(x, 3) { wg[q][x] = e.cw[(size_t)(gc + q) * 3 + x]; wv[q][x] = e.cw[(size_t)(DFF + gc + q) * 3 + x]; }
;       float pg[4], cgv[4], ng[4], pvv[4], cv[4], nv[4];
;       const int lr0 = rb * 16;
;       {
;         const int lrp = lr0 > 0 ? lr0 - 1 : 0;
;         const uint2 a = *(const uint2*)(U + lrp * 256 + c4), b = *(const uint2*)(U + lrp * 256 + 128 + c4);
;         pg[0] = lo2f(a.x); pg[1] = hi2f(a.x); pg[2] = lo2f(a.y); pg[3] = hi2f(a.y);
;         pvv[0] = lo2f(b.x); pvv[1] = hi2f(b.x); pvv[2] = lo2f(b.y); pvv[3] = hi2f(b.y);
;         const uint2 c = *(const uint2*)(U + lr0 * 256 + c4), d = *(const uint2*)(U + lr0 * 256 + 128 + c4);
;         cgv[0] = lo2f(c.x); cgv[1] = hi2f(c.x); cgv[2] = lo2f(c.y); cgv[3] = hi2f(c.y);
;         cv[0] = lo2f(d.x); cv[1] = hi2f(d.x); cv[2] = lo2f(d.y); cv[3] = hi2f(d.y);
;       }
; #pragma unroll 2
;       for (int q = 0; q < 16; ++q) {
;         const int lr = lr0 + q;
;         const int lrn = lr < 255 ? lr + 1 : 255;
;         const uint2 a = *(const uint2*)(U + lrn * 256 + c4), b = *(const uint2*)(U + lrn * 256 + 128 + c4);
.LBB0_1110:
	s_or_b64 exec, exec, s[40:41]
	v_bfe_u32 v128, v152, 4, 4
	v_xor_b32_e32 v128, v128, v154
	v_lshlrev_b32_e32 v128, 4, v128
	v_lshlrev_b32_e32 v129, 15, v153
	v_lshlrev_b32_e32 v130, 9, v154
	v_add3_u32 v128, v128, v129, v130
	v_cvt_pk_bf16_f32 v124, v124, v125
	v_cvt_pk_bf16_f32 v125, v126, v127
	v_cvt_pk_bf16_f32 v126, v120, v121
	v_cvt_pk_bf16_f32 v116, v116, v117
	v_cvt_pk_bf16_f32 v117, v118, v119
	v_cvt_pk_bf16_f32 v118, v112, v113
	v_cvt_pk_bf16_f32 v108, v108, v109
	v_cvt_pk_bf16_f32 v109, v110, v111
	v_cvt_pk_bf16_f32 v110, v104, v105
	v_cvt_pk_bf16_f32 v100, v100, v101
	v_cvt_pk_bf16_f32 v101, v102, v103
	v_cvt_pk_bf16_f32 v102, v96, v97
	v_cvt_pk_bf16_f32 v92, v92, v93
	v_cvt_pk_bf16_f32 v93, v94, v95
	v_cvt_pk_bf16_f32 v94, v88, v89
	v_cvt_pk_bf16_f32 v84, v84, v85
	v_cvt_pk_bf16_f32 v85, v86, v87
	v_cvt_pk_bf16_f32 v86, v80, v81
	v_cvt_pk_bf16_f32 v76, v76, v77
	v_cvt_pk_bf16_f32 v77, v78, v79
	v_cvt_pk_bf16_f32 v78, v72, v73
	v_cvt_pk_bf16_f32 v68, v68, v69
	v_cvt_pk_bf16_f32 v69, v70, v71
	v_cvt_pk_bf16_f32 v70, v64, v65
	v_cvt_pk_bf16_f32 v71, v66, v67
	v_cvt_pk_bf16_f32 v60, v60, v61
	v_cvt_pk_bf16_f32 v61, v62, v63
	v_cvt_pk_bf16_f32 v62, v56, v57
	v_cvt_pk_bf16_f32 v63, v58, v59
	v_cvt_pk_bf16_f32 v52, v52, v53
	v_cvt_pk_bf16_f32 v53, v54, v55
	v_cvt_pk_bf16_f32 v54, v48, v49
	v_cvt_pk_bf16_f32 v55, v50, v51
	v_cvt_pk_bf16_f32 v44, v44, v45
	v_cvt_pk_bf16_f32 v45, v46, v47
	v_cvt_pk_bf16_f32 v46, v40, v41
	v_cvt_pk_bf16_f32 v47, v42, v43
	v_cvt_pk_bf16_f32 v36, v36, v37
	v_cvt_pk_bf16_f32 v37, v38, v39
	v_cvt_pk_bf16_f32 v38, v32, v33
	v_cvt_pk_bf16_f32 v39, v34, v35
	v_cvt_pk_bf16_f32 v28, v28, v29
	v_cvt_pk_bf16_f32 v29, v30, v31
	v_cvt_pk_bf16_f32 v30, v24, v25
	v_cvt_pk_bf16_f32 v31, v26, v27
	v_cvt_pk_bf16_f32 v20, v20, v21
	v_cvt_pk_bf16_f32 v21, v22, v23
	v_cvt_pk_bf16_f32 v22, v16, v17
	v_cvt_pk_bf16_f32 v23, v18, v19
	v_cvt_pk_bf16_f32 v12, v12, v13
	v_cvt_pk_bf16_f32 v13, v14, v15
	v_cvt_pk_bf16_f32 v14, v8, v9
	v_cvt_pk_bf16_f32 v15, v10, v11
	v_cvt_pk_bf16_f32 v4, v4, v5
	v_cvt_pk_bf16_f32 v5, v6, v7
	v_cvt_pk_bf16_f32 v127, v122, v123
	v_cvt_pk_bf16_f32 v119, v114, v115
	v_cvt_pk_bf16_f32 v111, v106, v107
	v_cvt_pk_bf16_f32 v103, v98, v99
	v_cvt_pk_bf16_f32 v95, v90, v91
	v_cvt_pk_bf16_f32 v87, v82, v83
	v_cvt_pk_bf16_f32 v79, v74, v75
	v_cvt_pk_bf16_f32 v7, v2, v3
	v_cvt_pk_bf16_f32 v6, v0, v1
	v_add_u32_e32 v16, 0x14100, v128
	s_waitcnt lgkmcnt(0)
	s_barrier
	v_add_u32_e32 v32, 0x10100, v128
	ds_write_b128 v16, v[12:15]
	v_and_b32_e32 v16, 0x7c, v132
	v_add_u32_e32 v64, 0x10000, v128
	v_add_u32_e32 v56, 0x12000, v128
	v_add_u32_e32 v48, 0x14000, v128
	v_add_u32_e32 v40, 0x16000, v128
	ds_write_b128 v32, v[28:31]
	v_add_u32_e32 v24, 0x12100, v128
	v_add_u32_e32 v8, 0x16100, v128
	v_lshl_or_b32 v32, s51, 7, v16
	ds_write_b128 v128, v[124:127]
	ds_write_b128 v128, v[116:119] offset:8192
	ds_write_b128 v128, v[108:111] offset:16384
	ds_write_b128 v128, v[100:103] offset:24576
	ds_write_b128 v128, v[92:95] offset:256
	ds_write_b128 v128, v[84:87] offset:8448
	ds_write_b128 v128, v[76:79] offset:16640
	ds_write_b128 v128, v[68:71] offset:24832
	ds_write_b128 v64, v[60:63]
	ds_write_b128 v56, v[52:55]
	ds_write_b128 v48, v[44:47]
	ds_write_b128 v40, v[36:39]
	ds_write_b128 v24, v[20:23]
	ds_write_b128 v8, v[4:7]
	v_add_u32_e32 v0, 0x1600, v32
	s_waitcnt lgkmcnt(0)
	s_barrier
	s_waitcnt vmcnt(0)
	v_mov_b32_e32 v24, v218
	v_mov_b32_e32 v25, v219
	v_mov_b32_e32 v26, v220
	v_mov_b32_e32 v27, v221
	v_mov_b32_e32 v0, v222
	v_mov_b32_e32 v1, v223
	v_mov_b32_e32 v2, v224
	v_mov_b32_e32 v3, v225
	v_mov_b32_e32 v4, v226
	v_mov_b32_e32 v5, v227
	v_mov_b32_e32 v6, v228
	v_mov_b32_e32 v7, v229
	v_mov_b32_e32 v8, v230
	v_mov_b32_e32 v9, v231
	v_mov_b32_e32 v10, v232
	v_mov_b32_e32 v11, v233
	v_mov_b32_e32 v28, v234
	v_mov_b32_e32 v29, v235
	v_mov_b32_e32 v30, v236
	v_mov_b32_e32 v31, v237
	v_mov_b32_e32 v12, v238
	v_mov_b32_e32 v13, v239
	v_mov_b32_e32 v14, v240
	v_mov_b32_e32 v15, v241
	v_ashrrev_i32_e32 v34, 1, v152
	v_and_b32_e32 v132, -16, v34
	v_mov_b32_e32 v17, 0xffffff00
	v_lshl_add_u32 v17, v132, 8, v17
	v_cmp_lt_i32_e32 vcc, 15, v34
	v_lshl_add_u32 v64, v16, 1, 0
	v_bfe_u32 v96, v152, 1, 4
	v_and_b32_e32 v97, 1, v152
	v_lshlrev_b32_e32 v97, 3, v97
	s_ashr_i32 s51, s50, 31
	v_cndmask_b32_e32 v17, 0, v17, vcc
	v_lshrrev_b32_e32 v98, 8, v17
	v_and_b32_e32 v98, 15, v98
	v_xor_b32_e32 v98, v98, v96
	v_lshl_add_u32 v98, v98, 4, v97
	v_lshl_add_u32 v16, v17, 1, v98
	ds_read2_b64 v[16:19], v16 offset1:32
	s_ashr_i32 s53, s52, 31
	s_add_u32 s56, s52, -1
	s_addc_u32 s57, s53, -1
	s_add_i32 s61, s52, -1
	s_waitcnt lgkmcnt(0)
	v_and_b32_e32 v56, 0xffff0000, v16
	v_lshlrev_b32_e32 v58, 16, v16
	v_lshl_add_u32 v98, v96, 4, v97
	v_lshl_add_u32 v16, v132, 9, v98
	ds_read2_b64 v[20:23], v16 offset1:32
	s_ashr_i32 s62, s61, 31
	v_ashrrev_i32_e32 v33, 31, v32
	v_cmp_lt_i32_e64 s[40:41], -1, v34
	s_sub_u32 s58, s50, s42
	v_ashrrev_i32_e32 v35, 31, v132
	v_mov_b32_e32 v34, v132
	s_waitcnt lgkmcnt(0)
	v_lshlrev_b32_e32 v47, 16, v21
	v_lshlrev_b32_e32 v46, 16, v20
	v_and_b32_e32 v45, 0xffff0000, v21
	v_and_b32_e32 v44, 0xffff0000, v20
	v_lshlrev_b32_e32 v50, 16, v22
	v_lshlrev_b32_e32 v51, 16, v23
	v_and_b32_e32 v49, 0xffff0000, v23
	v_and_b32_e32 v48, 0xffff0000, v22
	s_subb_u32 s59, s51, s43
	s_movk_i32 s63, 0x2c00
	v_lshlrev_b32_e32 v63, 16, v19
	v_lshlrev_b32_e32 v62, 16, v18
	v_and_b32_e32 v61, 0xffff0000, v19
	v_and_b32_e32 v60, 0xffff0000, v18
	v_and_b32_e32 v57, 0xffff0000, v17
	v_lshlrev_b32_e32 v59, 16, v17
	v_mov_b32_e32 v248, 0x3a27c5ac
	s_waitcnt vmcnt(0)
	v_mov_b32_e32 v16, v24
	v_mov_b32_e32 v20, v9
	v_mov_b32_e32 v21, v31
	v_mov_b32_e32 v9, v30
	v_mov_b32_e32 v22, v15
	v_mov_b32_e32 v23, v29
	v_mov_b32_e32 v15, v28
	v_lshl_add_u64 v[28:29], s[42:43], 0, v[34:35]
	v_lshlrev_b64 v[30:31], 1, v[32:33]
	v_mov_b32_e32 v18, v7
	v_mov_b32_e32 v19, v1
	v_mov_b32_e32 v7, v0
	v_mov_b32_e32 v0, v13
	v_mov_b32_e32 v1, v11
	v_mov_b32_e32 v13, v10
	v_mov_b32_e32 v11, s59
	v_sub_co_u32_e32 v10, vcc, s58, v132
	v_mad_u64_u32 v[30:31], s[58:59], v28, s63, v[30:31]
	v_mov_b32_e32 v32, v31
	s_sub_u32 s42, s61, s42
	v_subb_co_u32_e32 v11, vcc, v11, v35, vcc
	v_mad_u64_u32 v[32:33], s[58:59], v29, s63, v[32:33]
	s_subb_u32 s43, s62, s43
	v_mov_b32_e32 v31, v32
	v_readlane_b32 s58, v254, 38
	v_mov_b32_e32 v33, s43
	v_sub_co_u32_e32 v32, vcc, s42, v132
	v_readlane_b32 s59, v254, 39
	s_nop 0
	v_subb_co_u32_e32 v33, vcc, v33, v35, vcc
	v_mov_b32_e32 v17, v2
	v_mov_b32_e32 v2, v25
	v_mov_b32_e32 v24, v5
	v_mov_b32_e32 v25, v27
	v_mov_b32_e32 v5, v26
	v_lshl_add_u64 v[26:27], v[10:11], 0, -1
	v_lshl_add_u64 v[30:31], s[58:59], 0, v[30:31]
	v_lshl_add_u64 v[34:35], v[32:33], 0, -1
	s_mov_b64 s[58:59], 0
	v_min_i32_e32 v98, 0xfe, v132
	v_add_u32_e32 v98, 1, v98
	v_and_b32_e32 v99, 15, v98
	v_xor_b32_e32 v99, v99, v96
	v_lshl_add_u32 v99, v99, 4, v97
	v_lshl_add_u32 v99, v98, 9, v99
	ds_read2_b64 v[100:103], v99 offset1:32
	s_branch .LBB0_1112

; #define UFOR(v, n) _Pragma("unroll") for (int v = 0; v < (n); ++v)
; __device__ __forceinline__ unsigned pk2(float a, float b) { return (unsigned)f2bf(a) | ((unsigned)f2bf(b) << 16); }
; __device__ __forceinline__ float lo2f(unsigned u) { return __uint_as_float(u << 16); }
; __device__ __forceinline__ float hi2f(unsigned u) { return __uint_as_float(u & 0xffff0000u); }
; __device__ __forceinline__ float siluf_(float x) { return x / (1.f + __expf(-x)); }
; template <int EPI, int K, int KL> ...
;     ...
;       for (int q = 0; q < 16; ++q) {
;         const int lr = lr0 + q;
;         const int lrn = lr < 255 ? lr + 1 : 255;
;         const uint2 a = *(const uint2*)(U + lrn * 256 + c4), b = *(const uint2*)(U + lrn * 256 + 128 + c4);
;         ng[0] = lo2f(a.x); ng[1] = hi2f(a.x); ng[2] = lo2f(a.y); ng[3] = hi2f(a.y);
;         nv[0] = lo2f(b.x); nv[1] = hi2f(b.x); nv[2] = lo2f(b.y); nv[3] = hi2f(b.y);
;         const long gr = brow + lr;
;         const bool valid = (gr >= seq0) && (gr < seq1) && (lr >= 1 || gr == seq0) && (lr <= 254 || gr == seq1 - 1);
;         if (valid) {
;           const float mp = (gr - 1 >= seq0) ? 1.f : 0.f, mn = (gr + 1 < seq1) ? 1.f : 0.f;
;           float o[4];
;           UFOR(x, 4) {
;             const float g = wg[x][0] * pg[x] * mp + wg[x][1] * cgv[x] + wg[x][2] * ng[x] * mn;
;             const float v = wv[x][0] * pvv[x] * mp + wv[x][1] * cv[x] + wv[x][2] * nv[x] * mn;
;             o[x] = siluf_(g) * v;
;           }
;           uint2 pk; pk.x = pk2(o[0], o[1]); pk.y = pk2(o[2], o[3]);
;           *(uint2*)(e.h2 + (size_t)gr * DFF + gc) = pk;
;         }
.LBB0_1112:
	v_lshl_add_u64 v[52:53], v[132:133], 0, s[58:59]
	v_lshl_add_u64 v[54:55], v[28:29], 0, s[58:59]
	v_cmp_le_i64_e32 vcc, s[50:51], v[54:55]
	v_cmp_gt_i64_e64 s[42:43], s[52:53], v[54:55]
	s_and_b64 s[62:63], vcc, s[42:43]
	v_cmp_lt_i32_e32 vcc, 0, v52
	v_cmp_eq_u64_e64 s[42:43], s[58:59], v[10:11]
	s_or_b64 s[42:43], vcc, s[42:43]
	s_and_b64 s[62:63], s[62:63], s[42:43]
	v_cmp_gt_i32_e32 vcc, s27, v52
	v_cmp_eq_u64_e64 s[42:43], s[58:59], v[32:33]
	s_or_b64 s[42:43], vcc, s[42:43]
	s_waitcnt lgkmcnt(0)
	v_lshlrev_b32_e32 v36, 16, v100
	v_lshlrev_b32_e32 v37, 16, v101
	v_and_b32_e32 v39, 0xffff0000, v101
	v_and_b32_e32 v38, 0xffff0000, v100
	v_lshlrev_b32_e32 v40, 16, v102
	v_lshlrev_b32_e32 v41, 16, v103
	v_and_b32_e32 v43, 0xffff0000, v103
	v_and_b32_e32 v42, 0xffff0000, v102
	v_add_u32_e32 v98, 1, v52
	v_min_i32_e32 v98, 0xfe, v98
	v_add_u32_e32 v98, 1, v98
	v_and_b32_e32 v99, 15, v98
	v_xor_b32_e32 v99, v99, v96
	v_lshl_add_u32 v99, v99, 4, v97
	v_lshl_add_u32 v99, v98, 9, v99
	ds_read2_b64 v[104:107], v99 offset1:32
	s_and_b64 s[62:63], s[62:63], s[42:43]
	s_and_saveexec_b64 s[42:43], s[62:63]
	s_cbranch_execz .LBB0_1114
	v_cmp_lt_i64_e32 vcc, s[50:51], v[54:55]
	v_pk_mul_f32 v[58:59], v[12:13], v[58:59]
	v_pk_mul_f32 v[56:57], v[22:23], v[56:57]
	v_cndmask_b32_e64 v66, 0, 1.0, vcc
	v_cmp_gt_i64_e32 vcc, s[56:57], v[54:55]
	v_pk_mul_f32 v[58:59], v[58:59], v[66:67] op_sel_hi:[1,0]
	v_pk_mul_f32 v[70:71], v[14:15], v[36:37]
	v_cndmask_b32_e64 v68, 0, 1.0, vcc
	v_pk_fma_f32 v[58:59], v[0:1], v[46:47], v[58:59]
	v_pk_mul_f32 v[56:57], v[56:57], v[66:67] op_sel_hi:[1,0]
	v_pk_mul_f32 v[74:75], v[20:21], v[38:39]
	v_pk_fma_f32 v[58:59], v[70:71], v[68:69], v[58:59] op_sel_hi:[1,0,1]
	v_pk_fma_f32 v[56:57], v[8:9], v[44:45], v[56:57]
	v_mul_f32_e32 v53, 0xbfb8aa3b, v58
	v_pk_fma_f32 v[56:57], v[74:75], v[68:69], v[56:57] op_sel_hi:[1,0,1]
	v_exp_f32_e32 v70, v53
	v_mul_f32_e32 v53, 0xbfb8aa3b, v56
	v_exp_f32_e32 v74, v53
	v_mul_f32_e32 v53, 0xbfb8aa3b, v59
	v_exp_f32_e32 v71, v53
	v_pk_mul_f32 v[62:63], v[4:5], v[62:63]
	v_pk_mul_f32 v[72:73], v[6:7], v[40:41]
	v_pk_mul_f32 v[62:63], v[62:63], v[66:67] op_sel_hi:[1,0]
	v_pk_add_f32 v[70:71], v[70:71], 1.0 op_sel_hi:[1,0]
	v_pk_fma_f32 v[62:63], v[24:25], v[50:51], v[62:63]
	v_pk_fma_f32 v[62:63], v[68:69], v[72:73], v[62:63] op_sel_hi:[0,1,1]
	v_pk_mul_f32 v[60:61], v[18:19], v[60:61]
	v_pk_mul_f32 v[76:77], v[2:3], v[42:43]
	s_nop 0
	v_div_scale_f32 v80, vcc, v70, v70, v58
	v_div_scale_f32 v81, vcc, v71, v71, v59
	v_rcp_f32_e32 v82, v80
	v_rcp_f32_e32 v83, v81
	v_div_scale_f32 v86, s[62:63], v58, v70, v58
	v_div_scale_f32 v87, vcc, v59, v71, v59
	v_pk_fma_f32 v[84:85], v[80:81], v[82:83], 1.0 op_sel_hi:[1,1,0] neg_lo:[1,0,0] neg_hi:[1,0,0]
	v_pk_fma_f32 v[82:83], v[84:85], v[82:83], v[82:83]
	v_pk_mul_f32 v[88:89], v[86:87], v[82:83]
	v_pk_fma_f32 v[84:85], v[80:81], v[88:89], v[86:87] neg_lo:[1,0,0] neg_hi:[1,0,0]
	v_pk_fma_f32 v[88:89], v[84:85], v[82:83], v[88:89]
	v_pk_fma_f32 v[84:85], v[80:81], v[88:89], v[86:87] neg_lo:[1,0,0] neg_hi:[1,0,0]
	v_div_fmas_f32 v85, v85, v83, v89
	s_mov_b64 vcc, s[62:63]
	s_nop 0
	v_div_fmas_f32 v84, v84, v82, v88
	v_div_fixup_f32 v59, v85, v71, v59
	v_div_fixup_f32 v58, v84, v70, v58
	v_mul_f32_e32 v53, 0xbfb8aa3b, v57
	v_exp_f32_e32 v75, v53
	v_pk_mul_f32 v[58:59], v[62:63], v[58:59]
	v_pk_mul_f32 v[60:61], v[60:61], v[66:67] op_sel_hi:[1,0]
	v_pk_add_f32 v[62:63], v[74:75], 1.0 op_sel_hi:[1,0]
	s_nop 0
	v_pk_fma_f32 v[60:61], v[16:17], v[48:49], v[60:61]
	v_pk_fma_f32 v[60:61], v[68:69], v[76:77], v[60:61] op_sel_hi:[0,1,1]
	s_nop 0
	v_div_scale_f32 v80, vcc, v62, v62, v56
	v_div_scale_f32 v81, vcc, v63, v63, v57
	v_rcp_f32_e32 v82, v80
	v_rcp_f32_e32 v83, v81
	v_div_scale_f32 v86, s[62:63], v56, v62, v56
	v_div_scale_f32 v87, vcc, v57, v63, v57
	v_pk_fma_f32 v[84:85], v[80:81], v[82:83], 1.0 op_sel_hi:[1,1,0] neg_lo:[1,0,0] neg_hi:[1,0,0]
	v_pk_fma_f32 v[82:83], v[84:85], v[82:83], v[82:83]
	v_pk_mul_f32 v[88:89], v[86:87], v[82:83]
	v_pk_fma_f32 v[84:85], v[80:81], v[88:89], v[86:87] neg_lo:[1,0,0] neg_hi:[1,0,0]
	v_pk_fma_f32 v[88:89], v[84:85], v[82:83], v[88:89]
	v_pk_fma_f32 v[84:85], v[80:81], v[88:89], v[86:87] neg_lo:[1,0,0] neg_hi:[1,0,0]
	v_div_fmas_f32 v85, v85, v83, v89
	s_mov_b64 vcc, s[62:63]
	s_nop 0
	v_div_fmas_f32 v84, v84, v82, v88
	v_div_fixup_f32 v57, v85, v63, v57
	v_div_fixup_f32 v56, v84, v62, v56
	v_pk_mul_f32 v[56:57], v[60:61], v[56:57]
	v_cvt_pk_bf16_f32 v56, v58, v56
	v_cvt_pk_bf16_f32 v57, v59, v57
	v_add_co_u32_e32 v58, vcc, 0xffffe000, v30
	s_nop 1
	v_addc_co_u32_e32 v59, vcc, -1, v31, vcc
	global_store_dwordx2 v[58:59], v[56:57], off offset:-3072
; #define UFOR(v, n) _Pragma("unroll") for (int v = 0; v < (n); ++v)
; __device__ __forceinline__ unsigned pk2(float a, float b) { return (unsigned)f2bf(a) | ((unsigned)f2bf(b) << 16); }
; __device__ __forceinline__ float lo2f(unsigned u) { return __uint_as_float(u << 16); }
; __device__ __forceinline__ float hi2f(unsigned u) { return __uint_as_float(u & 0xffff0000u); }
; __device__ __forceinline__ float siluf_(float x) { return x / (1.f + __expf(-x)); }
; template <int EPI, int K, int KL> ...
;     ...
;       for (int q = 0; q < 16; ++q) {
;         const int lr = lr0 + q;
;         const int lrn = lr < 255 ? lr + 1 : 255;
;         const uint2 a = *(const uint2*)(U + lrn * 256 + c4), b = *(const uint2*)(U + lrn * 256 + 128 + c4);
;         ng[0] = lo2f(a.x); ng[1] = hi2f(a.x); ng[2] = lo2f(a.y); ng[3] = hi2f(a.y);
;         nv[0] = lo2f(b.x); nv[1] = hi2f(b.x); nv[2] = lo2f(b.y); nv[3] = hi2f(b.y);
;         const long gr = brow + lr;
;         const bool valid = (gr >= seq0) && (gr < seq1) && (lr >= 1 || gr == seq0) && (lr <= 254 || gr == seq1 - 1);
;         if (valid) {
;           const float mp = (gr - 1 >= seq0) ? 1.f : 0.f, mn = (gr + 1 < seq1) ? 1.f : 0.f;
;           float o[4];
;           UFOR(x, 4) {
;             const float g = wg[x][0] * pg[x] * mp + wg[x][1] * cgv[x] + wg[x][2] * ng[x] * mn;
;             const float v = wv[x][0] * pvv[x] * mp + wv[x][1] * cv[x] + wv[x][2] * nv[x] * mn;
;             o[x] = siluf_(g) * v;
;           }
;           uint2 pk; pk.x = pk2(o[0], o[1]); pk.y = pk2(o[2], o[3]);
;           *(uint2*)(e.h2 + (size_t)gr * DFF + gc) = pk;
;         }
;         UFOR(x, 4) { pg[x] = cgv[x]; cgv[x] = ng[x]; pvv[x] = cv[x]; cv[x] = nv[x]; }
;       }
.LBB0_1114:
	s_or_b64 exec, exec, s[42:43]
	v_add_u32_e32 v62, 1, v52
	v_add_u32_e32 v98, 2, v52
	v_min_i32_e32 v98, 0xfe, v98
	v_add_u32_e32 v98, 1, v98
	v_lshl_add_u64 v[54:55], v[54:55], 0, 1
	v_cmp_le_i64_e32 vcc, s[50:51], v[54:55]
	v_cmp_gt_i64_e64 s[42:43], s[52:53], v[54:55]
	s_and_b64 s[42:43], vcc, s[42:43]
	v_cmp_eq_u64_e32 vcc, s[58:59], v[26:27]
	s_or_b64 s[62:63], s[40:41], vcc
	s_and_b64 s[62:63], s[42:43], s[62:63]
	v_cmp_gt_i32_e32 vcc, s27, v62
	v_cmp_eq_u64_e64 s[42:43], s[58:59], v[34:35]
	s_or_b64 s[42:43], vcc, s[42:43]
	s_waitcnt lgkmcnt(0)
	v_lshlrev_b32_e32 v52, 16, v104
	v_lshlrev_b32_e32 v53, 16, v105
	v_and_b32_e32 v57, 0xffff0000, v105
	v_and_b32_e32 v56, 0xffff0000, v104
	v_lshlrev_b32_e32 v58, 16, v106
	v_lshlrev_b32_e32 v59, 16, v107
	v_and_b32_e32 v61, 0xffff0000, v107
	v_and_b32_e32 v60, 0xffff0000, v106
	v_and_b32_e32 v99, 15, v98
	v_xor_b32_e32 v99, v99, v96
	v_lshl_add_u32 v99, v99, 4, v97
	v_lshl_add_u32 v99, v98, 9, v99
	ds_read2_b64 v[100:103], v99 offset1:32
	s_and_b64 s[62:63], s[62:63], s[42:43]
	s_and_saveexec_b64 s[42:43], s[62:63]
	s_cbranch_execz .LBB0_1111
	v_cmp_lt_i64_e32 vcc, s[50:51], v[54:55]
	v_pk_mul_f32 v[46:47], v[12:13], v[46:47]
	v_pk_mul_f32 v[66:67], v[14:15], v[52:53]
	v_cndmask_b32_e64 v62, 0, 1.0, vcc
	v_cmp_gt_i64_e32 vcc, s[56:57], v[54:55]
	v_pk_mul_f32 v[46:47], v[46:47], v[62:63] op_sel_hi:[1,0]
	v_pk_mul_f32 v[44:45], v[22:23], v[44:45]
	v_cndmask_b32_e64 v54, 0, 1.0, vcc
	v_pk_fma_f32 v[46:47], v[0:1], v[36:37], v[46:47]
	v_pk_mul_f32 v[44:45], v[44:45], v[62:63] op_sel_hi:[1,0]
	v_pk_fma_f32 v[46:47], v[66:67], v[54:55], v[46:47] op_sel_hi:[1,0,1]
	v_pk_mul_f32 v[50:51], v[4:5], v[50:51]
	v_pk_mul_f32 v[70:71], v[20:21], v[56:57]
	v_mul_f32_e32 v55, 0xbfb8aa3b, v46
	v_pk_fma_f32 v[44:45], v[8:9], v[38:39], v[44:45]
	v_pk_mul_f32 v[50:51], v[50:51], v[62:63] op_sel_hi:[1,0]
	v_pk_fma_f32 v[44:45], v[70:71], v[54:55], v[44:45] op_sel_hi:[1,0,1]
	v_pk_mul_f32 v[68:69], v[6:7], v[58:59]
	v_exp_f32_e32 v66, v55
	v_mul_f32_e32 v55, 0xbfb8aa3b, v44
	v_pk_fma_f32 v[50:51], v[24:25], v[40:41], v[50:51]
	v_exp_f32_e32 v70, v55
	v_pk_fma_f32 v[50:51], v[54:55], v[68:69], v[50:51] op_sel_hi:[0,1,1]
	v_mul_f32_e32 v55, 0xbfb8aa3b, v47
	v_exp_f32_e32 v67, v55
	v_pk_mul_f32 v[48:49], v[18:19], v[48:49]
	v_pk_mul_f32 v[72:73], v[2:3], v[60:61]
	v_pk_add_f32 v[66:67], v[66:67], 1.0 op_sel_hi:[1,0]
	s_nop 0
	s_nop 0
	s_nop 0
	v_div_scale_f32 v80, vcc, v66, v66, v46
	v_div_scale_f32 v81, vcc, v67, v67, v47
	v_rcp_f32_e32 v82, v80
	v_rcp_f32_e32 v83, v81
	v_div_scale_f32 v86, s[62:63], v46, v66, v46
	v_div_scale_f32 v87, vcc, v47, v67, v47
	v_pk_fma_f32 v[84:85], v[80:81], v[82:83], 1.0 op_sel_hi:[1,1,0] neg_lo:[1,0,0] neg_hi:[1,0,0]
	v_pk_fma_f32 v[82:83], v[84:85], v[82:83], v[82:83]
	v_pk_mul_f32 v[88:89], v[86:87], v[82:83]
	v_pk_fma_f32 v[84:85], v[80:81], v[88:89], v[86:87] neg_lo:[1,0,0] neg_hi:[1,0,0]
	v_pk_fma_f32 v[88:89], v[84:85], v[82:83], v[88:89]
	v_pk_fma_f32 v[84:85], v[80:81], v[88:89], v[86:87] neg_lo:[1,0,0] neg_hi:[1,0,0]
	v_div_fmas_f32 v85, v85, v83, v89
	s_mov_b64 vcc, s[62:63]
	s_nop 0
	v_div_fmas_f32 v84, v84, v82, v88
	v_div_fixup_f32 v47, v85, v67, v47
	v_div_fixup_f32 v46, v84, v66, v46
	v_pk_mul_f32 v[46:47], v[50:51], v[46:47]
	v_mul_f32_e32 v50, 0xbfb8aa3b, v45
	v_exp_f32_e32 v71, v50
	v_pk_mul_f32 v[48:49], v[48:49], v[62:63] op_sel_hi:[1,0]
	v_pk_add_f32 v[50:51], v[70:71], 1.0 op_sel_hi:[1,0]
	v_pk_fma_f32 v[48:49], v[16:17], v[42:43], v[48:49]
	s_nop 0
	v_pk_fma_f32 v[48:49], v[54:55], v[72:73], v[48:49] op_sel_hi:[0,1,1]
	s_nop 0
	s_nop 0
	v_div_scale_f32 v80, vcc, v50, v50, v44
	v_div_scale_f32 v81, vcc, v51, v51, v45
	v_rcp_f32_e32 v82, v80
	v_rcp_f32_e32 v83, v81
	v_div_scale_f32 v86, s[62:63], v44, v50, v44
	v_div_scale_f32 v87, vcc, v45, v51, v45
	v_pk_fma_f32 v[84:85], v[80:81], v[82:83], 1.0 op_sel_hi:[1,1,0] neg_lo:[1,0,0] neg_hi:[1,0,0]
	v_pk_fma_f32 v[82:83], v[84:85], v[82:83], v[82:83]
	v_pk_mul_f32 v[88:89], v[86:87], v[82:83]
	v_pk_fma_f32 v[84:85], v[80:81], v[88:89], v[86:87] neg_lo:[1,0,0] neg_hi:[1,0,0]
	v_pk_fma_f32 v[88:89], v[84:85], v[82:83], v[88:89]
	v_pk_fma_f32 v[84:85], v[80:81], v[88:89], v[86:87] neg_lo:[1,0,0] neg_hi:[1,0,0]
	v_div_fmas_f32 v85, v85, v83, v89
	s_mov_b64 vcc, s[62:63]
	s_nop 0
	v_div_fmas_f32 v84, v84, v82, v88
	v_div_fixup_f32 v45, v85, v51, v45
	v_div_fixup_f32 v44, v84, v50, v44
	v_pk_mul_f32 v[44:45], v[48:49], v[44:45]
	v_cvt_pk_bf16_f32 v45, v47, v45
	v_cvt_pk_bf16_f32 v44, v46, v44
	global_store_dwordx2 v[30:31], v[44:45], off
	s_branch .LBB0_1111
